# chain loop v3: scalar index math and prefetch loads hoisted to phase top, staging chunks interleaved later into LDS waits
# speedup vs baseline: 1.0061x; 1.0007x over previous
.LBB0_503:
	v_pk_mul_f32 v[0:1], v[108:109], v[92:93]
	v_pk_mul_f32 v[4:5], v[108:109], v[64:65]
	v_pk_mul_f32 v[8:9], v[108:109], v[68:69]
	v_mov_b32_e32 v99, v98
	s_waitcnt lgkmcnt(0)
	s_barrier
	s_add_i32 s27, s26, 2
	s_cmp_lt_u32 s26, 31
	s_cselect_b64 s[14:15], -1, 0
	s_and_b64 s[28:29], s[14:15], exec
	s_cselect_b32 s12, s27, 32
	s_add_i32 s30, s12, -2
	s_sub_i32 s12, 33, s12
	s_and_b64 s[28:29], s[2:3], exec
	s_cselect_b32 s12, s30, s12
	s_lshl_b32 s12, s12, 7
	s_add_i32 s12, s12, s16
	v_mad_i64_i32 v[234:235], s[28:29], s12, v129, v[112:113]
	v_lshl_add_u64 v[236:237], v[234:235], 0, s[4:5]
	v_lshl_add_u64 v[238:239], v[234:235], 0, s[8:9]
	v_lshl_add_u64 v[252:253], v[234:235], 0, s[10:11]
	global_load_dwordx4 v[170:173], v[234:235], off offset:1024
	global_load_dwordx4 v[174:177], v[234:235], off offset:2048
	global_load_dwordx4 v[178:181], v[236:237], off offset:1024
	global_load_dwordx4 v[182:185], v[236:237], off offset:2048
	global_load_dwordx4 v[186:189], v[238:239], off offset:1024
	global_load_dwordx4 v[190:193], v[238:239], off offset:2048
	global_load_dwordx4 v[194:197], v[252:253], off offset:1024
	global_load_dwordx4 v[198:201], v[252:253], off offset:2048
	v_pk_mul_f32 v[2:3], v[98:99], v[94:95]
	ds_read_b64_tr_b16 v[12:13], v127 offset:1216
	ds_read_b64_tr_b16 v[10:11], v127
	ds_read_b64_tr_b16 v[14:15], v127 offset:32
	ds_read_b64_tr_b16 v[18:19], v127 offset:64
	ds_read_b64_tr_b16 v[22:23], v127 offset:96
	ds_read_b64_tr_b16 v[28:29], v128 offset:1216
	ds_read_b64_tr_b16 v[26:27], v128
	ds_read_b64_tr_b16 v[16:17], v127 offset:1248
	ds_read_b64_tr_b16 v[20:21], v127 offset:1280
	ds_read_b64_tr_b16 v[24:25], v127 offset:1312
	ds_read_b64_tr_b16 v[94:95], v128 offset:1248
	ds_read_b64_tr_b16 v[92:93], v128 offset:32
	v_pk_mul_f32 v[6:7], v[98:99], v[66:67]
	s_waitcnt lgkmcnt(5)
	v_mfma_f32_16x16x32_bf16 v[0:3], v[10:13], v[26:29], v[0:3]
	v_mul_f32_e64 v64, v108, v72
	v_mul_f32_e64 v65, v109, v73
	v_pk_mul_f32 v[66:67], v[98:99], v[74:75]
	v_pk_mul_f32 v[68:69], v[108:109], v[76:77]
	s_waitcnt lgkmcnt(0)
	v_mfma_f32_16x16x32_bf16 v[4:7], v[10:13], v[92:95], v[4:7]
	v_mul_f32_e64 v10, v98, v70
	v_mul_f32_e64 v11, v99, v71
	v_pk_mul_f32 v[12:13], v[108:109], v[80:81]
	v_pk_mul_f32 v[72:73], v[108:109], v[84:85]
	v_mfma_f32_16x16x32_bf16 v[8:11], v[14:17], v[26:29], v[8:11]
	v_mul_f32_e64 v76, v108, v88
	v_mul_f32_e64 v77, v109, v89
	v_pk_mul_f32 v[70:71], v[98:99], v[78:79]
	v_pk_mul_f32 v[74:75], v[98:99], v[86:87]
	v_mfma_f32_16x16x32_bf16 v[64:67], v[14:17], v[92:95], v[64:67]
	v_mul_f32_e64 v14, v98, v82
	v_mul_f32_e64 v15, v99, v83
	v_pk_mul_f32 v[78:79], v[98:99], v[90:91]
	ds_read_b64_tr_b16 v[16:17], v127 offset:9728
	ds_read_b64_tr_b16 v[80:81], v127 offset:9760
	ds_read_b64_tr_b16 v[84:85], v127 offset:9792
	v_mfma_f32_16x16x32_bf16 v[68:71], v[18:21], v[26:29], v[68:71]
	s_nop 2
	v_mfma_f32_16x16x32_bf16 v[12:15], v[18:21], v[92:95], v[12:15]
	ds_read_b64_tr_b16 v[18:19], v127 offset:10944
	ds_read_b64_tr_b16 v[82:83], v127 offset:10976
	ds_read_b64_tr_b16 v[86:87], v127 offset:11008
	s_nop 1
	v_mfma_f32_16x16x32_bf16 v[26:29], v[22:25], v[26:29], v[72:75]
	ds_read_b64_tr_b16 v[20:21], v127 offset:9824
	s_nop 1
	ds_read_b64_tr_b16 v[72:73], v128 offset:9728
	ds_read_b64_tr_b16 v[74:75], v128 offset:10944
	s_nop 1
	v_mfma_f32_16x16x32_bf16 v[76:79], v[22:25], v[92:95], v[76:79]
	ds_read_b64_tr_b16 v[22:23], v127 offset:11040
	ds_read_b64_tr_b16 v[90:91], v128 offset:10976
	ds_read_b64_tr_b16 v[88:89], v128 offset:9760
	s_nop 1
	s_waitcnt lgkmcnt(3)
	v_mfma_f32_16x16x32_bf16 v[0:3], v[16:19], v[72:75], v[0:3]
	s_nop 1
	s_add_i32 s30, s24, 1
	s_waitcnt lgkmcnt(0)
	v_mfma_f32_16x16x32_bf16 v[4:7], v[16:19], v[88:91], v[4:7]
	v_mov_b32_e32 v115, v97
	v_mov_b32_e32 v117, v97
	v_mfma_f32_16x16x32_bf16 v[16:19], v[80:83], v[88:91], v[64:67]
	s_nop 2
	ds_read_b64_tr_b16 v[64:65], v127 offset:19456
	v_mfma_f32_16x16x32_bf16 v[8:11], v[80:83], v[72:75], v[8:11]
	ds_read_b64_tr_b16 v[66:67], v127 offset:20672
	ds_read_b64_tr_b16 v[82:83], v127 offset:20704
	ds_read_b64_tr_b16 v[94:95], v127 offset:20736
	v_mfma_f32_16x16x32_bf16 v[68:71], v[84:87], v[72:75], v[68:71]
	v_mfma_f32_16x16x32_bf16 v[12:15], v[84:87], v[88:91], v[12:15]
	ds_read_b64_tr_b16 v[80:81], v127 offset:19488
	ds_read_b64_tr_b16 v[92:93], v127 offset:19520
	ds_read_b64_tr_b16 v[84:85], v127 offset:19552
	v_mfma_f32_16x16x32_bf16 v[24:27], v[20:23], v[72:75], v[26:29]
	ds_read_b64_tr_b16 v[86:87], v127 offset:20768
	ds_read_b64_tr_b16 v[72:73], v128 offset:19456
	ds_read_b64_tr_b16 v[74:75], v128 offset:20672
	v_mfma_f32_16x16x32_bf16 v[20:23], v[20:23], v[88:91], v[76:79]
	s_nop 2
	ds_read_b64_tr_b16 v[78:79], v128 offset:20704
	ds_read_b64_tr_b16 v[76:77], v128 offset:19488
	ds_read_b64_tr_b16 v[88:89], v127 offset:29184
	ds_read_b64_tr_b16 v[90:91], v127 offset:30400
	ds_read_b64_tr_b16 v[132:133], v127 offset:30432
	ds_read_b64_tr_b16 v[136:137], v127 offset:30464
	ds_read_b64_tr_b16 v[130:131], v127 offset:29216
	ds_read_b64_tr_b16 v[134:135], v127 offset:29248
	ds_read_b64_tr_b16 v[138:139], v127 offset:29280
	ds_read_b64_tr_b16 v[140:141], v127 offset:30496
	ds_read_b64_tr_b16 v[146:147], v128 offset:29184
	ds_read_b64_tr_b16 v[148:149], v128 offset:30400
	s_waitcnt vmcnt(22)
	v_add_u32_e32 v250, v118, v123
	v_lshlrev_b32_e32 v242, 16, v206
	v_and_b32_e32 v243, 0xffff0000, v206
	v_lshlrev_b32_e32 v244, 16, v207
	v_and_b32_e32 v245, 0xffff0000, v207
	v_lshlrev_b32_e32 v246, 16, v208
	v_and_b32_e32 v247, 0xffff0000, v208
	v_lshlrev_b32_e32 v248, 16, v209
	v_and_b32_e32 v249, 0xffff0000, v209
	v_pk_mul_f32 v[242:243], v[100:101], v[242:243]
	v_pk_mul_f32 v[244:245], v[100:101], v[244:245]
	v_pk_mul_f32 v[246:247], v[100:101], v[246:247]
	v_pk_mul_f32 v[248:249], v[100:101], v[248:249]
	v_cvt_pk_bf16_f32 v206, v242, v243
	v_cvt_pk_bf16_f32 v207, v244, v245
	v_cvt_pk_bf16_f32 v208, v246, v247
	v_cvt_pk_bf16_f32 v209, v248, v249
	ds_write_b128 v250, v[202:205]
	ds_write_b128 v250, v[206:209] offset:38912
	s_waitcnt lgkmcnt(14)
	v_mfma_f32_16x16x32_bf16 v[0:3], v[64:67], v[72:75], v[0:3]
	ds_read_b64_tr_b16 v[152:153], v128 offset:30432
	ds_read_b64_tr_b16 v[150:151], v128 offset:29216
	s_waitcnt vmcnt(20)
	v_lshlrev_b32_e32 v242, 16, v214
	v_and_b32_e32 v243, 0xffff0000, v214
	v_lshlrev_b32_e32 v244, 16, v215
	v_and_b32_e32 v245, 0xffff0000, v215
	v_lshlrev_b32_e32 v246, 16, v216
	v_and_b32_e32 v247, 0xffff0000, v216
	v_lshlrev_b32_e32 v248, 16, v217
	v_and_b32_e32 v249, 0xffff0000, v217
	v_pk_mul_f32 v[242:243], v[102:103], v[242:243]
	v_pk_mul_f32 v[244:245], v[102:103], v[244:245]
	v_pk_mul_f32 v[246:247], v[102:103], v[246:247]
	v_pk_mul_f32 v[248:249], v[102:103], v[248:249]
	v_cvt_pk_bf16_f32 v214, v242, v243
	v_cvt_pk_bf16_f32 v215, v244, v245
	v_cvt_pk_bf16_f32 v216, v246, v247
	v_cvt_pk_bf16_f32 v217, v248, v249
	ds_write_b128 v250, v[210:213] offset:9728
	ds_write_b128 v250, v[214:217] offset:48640
	s_waitcnt lgkmcnt(15)
	v_mfma_f32_16x16x32_bf16 v[64:67], v[64:67], v[76:79], v[4:7]
	s_nop 2
	v_mfma_f32_16x16x32_bf16 v[142:145], v[80:83], v[72:75], v[8:11]
	s_add_i32 s12, s26, -1
	v_mfma_f32_16x16x32_bf16 v[80:83], v[80:83], v[76:79], v[16:19]
	s_and_b64 s[28:29], s[2:3], exec
	s_cselect_b32 s12, s12, s30
	s_add_i32 s12, s12, s17
	v_mfma_f32_16x16x32_bf16 v[154:157], v[92:95], v[72:75], v[68:71]
	s_lshl_b64 s[28:29], s[12:13], 15
	v_mfma_f32_16x16x32_bf16 v[162:165], v[92:95], v[76:79], v[12:15]
	s_nop 0
	v_mfma_f32_16x16x32_bf16 v[166:169], v[84:87], v[72:75], v[24:27]
	s_nop 2
	v_mfma_f32_16x16x32_bf16 v[84:87], v[84:87], v[76:79], v[20:23]
	s_nop 2
	s_nop 0
	s_nop 0
	s_waitcnt vmcnt(18)
	v_lshlrev_b32_e32 v242, 16, v222
	v_and_b32_e32 v243, 0xffff0000, v222
	v_lshlrev_b32_e32 v244, 16, v223
	v_and_b32_e32 v245, 0xffff0000, v223
	v_lshlrev_b32_e32 v246, 16, v224
	v_and_b32_e32 v247, 0xffff0000, v224
	v_lshlrev_b32_e32 v248, 16, v225
	v_and_b32_e32 v249, 0xffff0000, v225
	v_pk_mul_f32 v[242:243], v[104:105], v[242:243]
	v_pk_mul_f32 v[244:245], v[104:105], v[244:245]
	v_pk_mul_f32 v[246:247], v[104:105], v[246:247]
	v_pk_mul_f32 v[248:249], v[104:105], v[248:249]
	v_cvt_pk_bf16_f32 v222, v242, v243
	v_cvt_pk_bf16_f32 v223, v244, v245
	v_cvt_pk_bf16_f32 v224, v246, v247
	v_cvt_pk_bf16_f32 v225, v248, v249
	ds_write_b128 v250, v[218:221] offset:19456
	ds_write_b128 v250, v[222:225] offset:58368
	s_waitcnt lgkmcnt(4)
	v_mfma_f32_16x16x32_bf16 v[92:95], v[88:91], v[146:149], v[0:3]
	s_nop 2
	s_waitcnt vmcnt(16)
	v_lshlrev_b32_e32 v242, 16, v230
	v_and_b32_e32 v243, 0xffff0000, v230
	v_lshlrev_b32_e32 v244, 16, v231
	v_and_b32_e32 v245, 0xffff0000, v231
	v_lshlrev_b32_e32 v246, 16, v232
	v_and_b32_e32 v247, 0xffff0000, v232
	v_lshlrev_b32_e32 v248, 16, v233
	v_and_b32_e32 v249, 0xffff0000, v233
	v_pk_mul_f32 v[242:243], v[106:107], v[242:243]
	v_pk_mul_f32 v[244:245], v[106:107], v[244:245]
	v_pk_mul_f32 v[246:247], v[106:107], v[246:247]
	v_pk_mul_f32 v[248:249], v[106:107], v[248:249]
	v_cvt_pk_bf16_f32 v230, v242, v243
	v_cvt_pk_bf16_f32 v231, v244, v245
	v_cvt_pk_bf16_f32 v232, v246, v247
	v_cvt_pk_bf16_f32 v233, v248, v249
	ds_write_b128 v250, v[226:229] offset:29184
	ds_write_b128 v119, v[230:233] offset:58368
	s_waitcnt lgkmcnt(2)
	v_mfma_f32_16x16x32_bf16 v[68:71], v[130:133], v[150:153], v[80:83]
	s_nop 2
	v_lshl_add_u64 v[80:81], v[110:111], 0, s[28:29]
	v_mfma_f32_16x16x32_bf16 v[88:91], v[88:91], v[150:153], v[64:67]
	v_mfma_f32_16x16x32_bf16 v[64:67], v[130:133], v[146:149], v[142:145]
	v_lshl_add_u64 v[130:131], v[80:81], 0, v[96:97]
	v_lshl_add_u64 v[132:133], v[80:81], 0, v[114:115]
	v_mfma_f32_16x16x32_bf16 v[72:75], v[134:137], v[146:149], v[154:157]
	v_cvt_pk_bf16_f32 v144, v68, v69
	s_nop 3
	v_cvt_pk_bf16_f32 v142, v64, v65
	v_cvt_pk_bf16_f32 v143, v66, v67
	v_mfma_f32_16x16x32_bf16 v[76:79], v[134:137], v[150:153], v[162:165]
	v_lshl_add_u64 v[134:135], v[80:81], 0, v[116:117]
	v_add_co_u32_e32 v136, vcc, s25, v130
	v_mfma_f32_16x16x32_bf16 v[80:83], v[138:141], v[146:149], v[166:169]
	s_nop 0
	v_addc_co_u32_e32 v137, vcc, 0, v131, vcc
	v_cvt_pk_bf16_f32 v145, v70, v71
	v_mfma_f32_16x16x32_bf16 v[84:87], v[138:141], v[150:153], v[84:87]
	v_cvt_pk_bf16_f32 v138, v92, v93
	v_cvt_pk_bf16_f32 v139, v94, v95
	v_cvt_pk_bf16_f32 v140, v88, v89
	v_cvt_pk_bf16_f32 v141, v90, v91
	v_cvt_pk_bf16_f32 v146, v72, v73
	v_cvt_pk_bf16_f32 v147, v74, v75
	v_cvt_pk_bf16_f32 v148, v76, v77
	v_cvt_pk_bf16_f32 v149, v78, v79
	v_cvt_pk_bf16_f32 v150, v80, v81
	v_cvt_pk_bf16_f32 v151, v82, v83
	v_cvt_pk_bf16_f32 v152, v84, v85
	v_cvt_pk_bf16_f32 v153, v86, v87
	global_store_dwordx2 v[130:131], v[138:139], off
	global_store_dwordx2 v[136:137], v[140:141], off
	global_store_dwordx2 v[130:131], v[142:143], off offset:512
	global_store_dwordx2 v[132:133], v[144:145], off
	global_store_dwordx2 v[130:131], v[146:147], off offset:1024
	global_store_dwordx2 v[136:137], v[148:149], off offset:1024
	global_store_dwordx2 v[130:131], v[150:151], off offset:1536
	global_store_dwordx2 v[134:135], v[152:153], off
	v_pk_mul_f32 v[54:55], v[98:99], v[90:91]
	v_pk_mul_f32 v[52:53], v[108:109], v[88:89]
	v_pk_mul_f32 v[50:51], v[98:99], v[94:95]
	v_pk_mul_f32 v[48:49], v[108:109], v[92:93]
	v_add_u32_e32 v155, v120, v124
	s_waitcnt lgkmcnt(0)
	s_barrier
	s_min_u32 s12, s26, 29
	s_add_i32 s30, s12, 1
	s_sub_i32 s12, 30, s12
	s_and_b64 s[28:29], s[2:3], exec
	s_cselect_b32 s12, s30, s12
	s_lshl_b32 s12, s12, 7
	s_add_i32 s12, s12, s16
	s_mulk_i32 s12, 0x1c00
	v_lshl_add_u64 v[234:235], v[112:113], 0, s[12:13]
	v_lshl_add_u64 v[236:237], v[234:235], 0, s[4:5]
	v_lshl_add_u64 v[238:239], v[234:235], 0, s[8:9]
	v_lshl_add_u64 v[252:253], v[234:235], 0, s[10:11]
	global_load_dwordx4 v[202:205], v[234:235], off offset:1024
	global_load_dwordx4 v[206:209], v[234:235], off offset:2048
	global_load_dwordx4 v[210:213], v[236:237], off offset:1024
	global_load_dwordx4 v[214:217], v[236:237], off offset:2048
	global_load_dwordx4 v[218:221], v[238:239], off offset:1024
	global_load_dwordx4 v[222:225], v[238:239], off offset:2048
	global_load_dwordx4 v[226:229], v[252:253], off offset:1024
	global_load_dwordx4 v[230:233], v[252:253], off offset:2048
	v_add_u32_e32 v156, v121, v124
	ds_read_b64_tr_b16 v[34:35], v155 offset:1216
	ds_read_b64_tr_b16 v[32:33], v155
	ds_read_b64_tr_b16 v[36:37], v155 offset:32
	ds_read_b64_tr_b16 v[40:41], v155 offset:64
	ds_read_b64_tr_b16 v[44:45], v155 offset:96
	ds_read_b64_tr_b16 v[58:59], v156 offset:40128
	ds_read_b64_tr_b16 v[56:57], v156 offset:38912
	ds_read_b64_tr_b16 v[38:39], v155 offset:1248
	ds_read_b64_tr_b16 v[42:43], v155 offset:1280
	ds_read_b64_tr_b16 v[46:47], v155 offset:1312
	ds_read_b64_tr_b16 v[62:63], v156 offset:40160
	ds_read_b64_tr_b16 v[60:61], v156 offset:38944
	v_pk_mul_f32 v[66:67], v[98:99], v[66:67]
	v_pk_mul_f32 v[64:65], v[108:109], v[64:65]
	v_pk_mul_f32 v[70:71], v[98:99], v[70:71]
	v_pk_mul_f32 v[68:69], v[108:109], v[68:69]
	s_waitcnt lgkmcnt(5)
	v_mfma_f32_16x16x32_bf16 v[48:51], v[32:35], v[56:59], v[48:51]
	s_nop 2
	s_waitcnt lgkmcnt(0)
	v_mfma_f32_16x16x32_bf16 v[32:35], v[32:35], v[60:63], v[52:55]
	s_nop 2
	v_pk_mul_f32 v[54:55], v[98:99], v[74:75]
	v_pk_mul_f32 v[52:53], v[108:109], v[72:73]
	v_mfma_f32_16x16x32_bf16 v[64:67], v[36:39], v[56:59], v[64:67]
	v_mul_f32_e64 v74, v98, v78
	v_mul_f32_e64 v75, v99, v79
	v_pk_mul_f32 v[72:73], v[108:109], v[76:77]
	v_pk_mul_f32 v[78:79], v[98:99], v[82:83]
	v_mfma_f32_16x16x32_bf16 v[36:39], v[36:39], v[60:63], v[68:71]
	v_mul_f32_e64 v76, v108, v80
	v_mul_f32_e64 v77, v109, v81
	s_nop 1
	v_pk_mul_f32 v[70:71], v[98:99], v[86:87]
	v_pk_mul_f32 v[68:69], v[108:109], v[84:85]
	v_mfma_f32_16x16x32_bf16 v[52:55], v[40:43], v[56:59], v[52:55]
	ds_read_b64_tr_b16 v[80:81], v155 offset:9728
	ds_read_b64_tr_b16 v[84:85], v155 offset:9760
	ds_read_b64_tr_b16 v[88:89], v155 offset:9792
	ds_read_b64_tr_b16 v[82:83], v155 offset:10944
	ds_read_b64_tr_b16 v[86:87], v155 offset:10976
	ds_read_b64_tr_b16 v[90:91], v155 offset:11008
	s_and_b64 s[28:29], s[2:3], exec
	v_mfma_f32_16x16x32_bf16 v[40:43], v[40:43], v[60:63], v[72:75]
	v_mfma_f32_16x16x32_bf16 v[56:59], v[44:47], v[56:59], v[76:79]
	s_nop 1
	ds_read_b64_tr_b16 v[72:73], v155 offset:9824
	ds_read_b64_tr_b16 v[76:77], v156 offset:48640
	ds_read_b64_tr_b16 v[78:79], v156 offset:49856
	v_mfma_f32_16x16x32_bf16 v[44:47], v[44:47], v[60:63], v[68:71]
	ds_read_b64_tr_b16 v[74:75], v155 offset:11040
	ds_read_b64_tr_b16 v[62:63], v156 offset:49888
	ds_read_b64_tr_b16 v[60:61], v156 offset:48672
	s_waitcnt lgkmcnt(3)
	v_mfma_f32_16x16x32_bf16 v[48:51], v[80:83], v[76:79], v[48:51]
	s_waitcnt lgkmcnt(0)
	v_mfma_f32_16x16x32_bf16 v[32:35], v[80:83], v[60:63], v[32:35]
	v_mfma_f32_16x16x32_bf16 v[64:67], v[84:87], v[76:79], v[64:67]
	v_mfma_f32_16x16x32_bf16 v[36:39], v[84:87], v[60:63], v[36:39]
	ds_read_b64_tr_b16 v[68:69], v155 offset:19456
	ds_read_b64_tr_b16 v[80:81], v155 offset:19488
	ds_read_b64_tr_b16 v[84:85], v155 offset:19520
	ds_read_b64_tr_b16 v[70:71], v155 offset:20672
	ds_read_b64_tr_b16 v[82:83], v155 offset:20704
	ds_read_b64_tr_b16 v[86:87], v155 offset:20736
	v_mfma_f32_16x16x32_bf16 v[52:55], v[88:91], v[76:79], v[52:55]
	v_mfma_f32_16x16x32_bf16 v[40:43], v[88:91], v[60:63], v[40:43]
	v_mfma_f32_16x16x32_bf16 v[56:59], v[72:75], v[76:79], v[56:59]
	ds_read_b64_tr_b16 v[76:77], v155 offset:19552
	ds_read_b64_tr_b16 v[88:89], v156 offset:58368
	ds_read_b64_tr_b16 v[90:91], v156 offset:59584
	v_mfma_f32_16x16x32_bf16 v[44:47], v[72:75], v[60:63], v[44:47]
	ds_read_b64_tr_b16 v[78:79], v155 offset:20768
	ds_read_b64_tr_b16 v[62:63], v156 offset:59616
	ds_read_b64_tr_b16 v[60:61], v156 offset:58400
	s_waitcnt vmcnt(22)
	v_lshlrev_b32_e32 v242, 16, v174
	v_and_b32_e32 v243, 0xffff0000, v174
	v_lshlrev_b32_e32 v244, 16, v175
	v_and_b32_e32 v245, 0xffff0000, v175
	v_lshlrev_b32_e32 v246, 16, v176
	v_and_b32_e32 v247, 0xffff0000, v176
	v_lshlrev_b32_e32 v248, 16, v177
	v_and_b32_e32 v249, 0xffff0000, v177
	v_pk_mul_f32 v[242:243], v[100:101], v[242:243]
	v_pk_mul_f32 v[244:245], v[100:101], v[244:245]
	v_pk_mul_f32 v[246:247], v[100:101], v[246:247]
	v_pk_mul_f32 v[248:249], v[100:101], v[248:249]
	v_cvt_pk_bf16_f32 v174, v242, v243
	v_cvt_pk_bf16_f32 v175, v244, v245
	v_cvt_pk_bf16_f32 v176, v246, v247
	v_cvt_pk_bf16_f32 v177, v248, v249
	ds_write_b128 v125, v[170:173]
	ds_write_b128 v126, v[174:177]
	s_waitcnt lgkmcnt(5)
	v_mfma_f32_16x16x32_bf16 v[72:75], v[80:83], v[88:91], v[64:67]
	s_waitcnt vmcnt(20)
	v_lshlrev_b32_e32 v242, 16, v182
	v_and_b32_e32 v243, 0xffff0000, v182
	v_lshlrev_b32_e32 v244, 16, v183
	v_and_b32_e32 v245, 0xffff0000, v183
	v_lshlrev_b32_e32 v246, 16, v184
	v_and_b32_e32 v247, 0xffff0000, v184
	v_lshlrev_b32_e32 v248, 16, v185
	v_and_b32_e32 v249, 0xffff0000, v185
	v_pk_mul_f32 v[242:243], v[102:103], v[242:243]
	v_pk_mul_f32 v[244:245], v[102:103], v[244:245]
	v_pk_mul_f32 v[246:247], v[102:103], v[246:247]
	v_pk_mul_f32 v[248:249], v[102:103], v[248:249]
	v_cvt_pk_bf16_f32 v182, v242, v243
	v_cvt_pk_bf16_f32 v183, v244, v245
	v_cvt_pk_bf16_f32 v184, v246, v247
	v_cvt_pk_bf16_f32 v185, v248, v249
	ds_write_b128 v125, v[178:181] offset:9728
	ds_write_b128 v126, v[182:185] offset:9728
	s_waitcnt lgkmcnt(4)
	v_mfma_f32_16x16x32_bf16 v[80:83], v[80:83], v[60:63], v[36:39]
	s_nop 2
	ds_read_b64_tr_b16 v[36:37], v155 offset:29184
	ds_read_b64_tr_b16 v[38:39], v155 offset:30400
	ds_read_b64_tr_b16 v[132:133], v155 offset:30432
	ds_read_b64_tr_b16 v[130:131], v155 offset:29216
	ds_read_b64_tr_b16 v[138:139], v155 offset:29248
	ds_read_b64_tr_b16 v[142:143], v155 offset:29280
	ds_read_b64_tr_b16 v[140:141], v155 offset:30464
	ds_read_b64_tr_b16 v[144:145], v155 offset:30496
	ds_read_b64_tr_b16 v[148:149], v122 offset:40128
	ds_read_b64_tr_b16 v[146:147], v122 offset:38912
	ds_read_b64_tr_b16 v[152:153], v122 offset:40160
	ds_read_b64_tr_b16 v[150:151], v122 offset:38944
	v_mfma_f32_16x16x32_bf16 v[48:51], v[68:71], v[88:91], v[48:51]
	v_mfma_f32_16x16x32_bf16 v[68:71], v[68:71], v[60:63], v[32:35]
	v_mfma_f32_16x16x32_bf16 v[134:137], v[84:87], v[88:91], v[52:55]
	v_mfma_f32_16x16x32_bf16 v[84:87], v[84:87], v[60:63], v[40:43]
	s_nop 2
	v_mfma_f32_16x16x32_bf16 v[154:157], v[76:79], v[60:63], v[44:47]
	v_mfma_f32_16x16x32_bf16 v[88:91], v[76:79], v[88:91], v[56:59]
	s_cselect_b32 s12, s26, s24
	s_add_i32 s12, s12, s17
	s_lshl_b64 s[28:29], s[12:13], 15
	s_waitcnt vmcnt(18)
	v_lshlrev_b32_e32 v242, 16, v190
	v_and_b32_e32 v243, 0xffff0000, v190
	v_lshlrev_b32_e32 v244, 16, v191
	v_and_b32_e32 v245, 0xffff0000, v191
	v_lshlrev_b32_e32 v246, 16, v192
	v_and_b32_e32 v247, 0xffff0000, v192
	v_lshlrev_b32_e32 v248, 16, v193
	v_and_b32_e32 v249, 0xffff0000, v193
	v_pk_mul_f32 v[242:243], v[104:105], v[242:243]
	v_pk_mul_f32 v[244:245], v[104:105], v[244:245]
	v_pk_mul_f32 v[246:247], v[104:105], v[246:247]
	v_pk_mul_f32 v[248:249], v[104:105], v[248:249]
	v_cvt_pk_bf16_f32 v190, v242, v243
	v_cvt_pk_bf16_f32 v191, v244, v245
	v_cvt_pk_bf16_f32 v192, v246, v247
	v_cvt_pk_bf16_f32 v193, v248, v249
	ds_write_b128 v125, v[186:189] offset:19456
	ds_write_b128 v126, v[190:193] offset:19456
	s_waitcnt lgkmcnt(4)
	v_mfma_f32_16x16x32_bf16 v[92:95], v[36:39], v[146:149], v[48:51]
	s_waitcnt vmcnt(16)
	v_lshlrev_b32_e32 v242, 16, v198
	v_and_b32_e32 v243, 0xffff0000, v198
	v_lshlrev_b32_e32 v244, 16, v199
	v_and_b32_e32 v245, 0xffff0000, v199
	v_lshlrev_b32_e32 v246, 16, v200
	v_and_b32_e32 v247, 0xffff0000, v200
	v_lshlrev_b32_e32 v248, 16, v201
	v_and_b32_e32 v249, 0xffff0000, v201
	v_pk_mul_f32 v[242:243], v[106:107], v[242:243]
	v_pk_mul_f32 v[244:245], v[106:107], v[244:245]
	v_pk_mul_f32 v[246:247], v[106:107], v[246:247]
	v_pk_mul_f32 v[248:249], v[106:107], v[248:249]
	v_cvt_pk_bf16_f32 v198, v242, v243
	v_cvt_pk_bf16_f32 v199, v244, v245
	v_cvt_pk_bf16_f32 v200, v246, v247
	v_cvt_pk_bf16_f32 v201, v248, v249
	ds_write_b128 v125, v[194:197] offset:29184
	ds_write_b128 v126, v[198:201] offset:29184
	s_waitcnt lgkmcnt(2)
	v_mfma_f32_16x16x32_bf16 v[64:67], v[36:39], v[150:153], v[68:71]
	s_nop 0
	s_nop 0
	s_nop 0
	v_mfma_f32_16x16x32_bf16 v[68:71], v[130:133], v[146:149], v[72:75]
	v_mfma_f32_16x16x32_bf16 v[72:75], v[130:133], v[150:153], v[80:83]
	v_lshl_add_u64 v[130:131], v[110:111], 0, s[28:29]
	v_lshl_add_u64 v[132:133], v[130:131], 0, v[96:97]
	v_mfma_f32_16x16x32_bf16 v[76:79], v[138:141], v[146:149], v[134:137]
	v_mfma_f32_16x16x32_bf16 v[80:83], v[138:141], v[150:153], v[84:87]
	s_nop 1
	v_add_co_u32_e32 v136, vcc, s25, v132
	v_cvt_pk_bf16_f32 v138, v92, v93
	v_mfma_f32_16x16x32_bf16 v[84:87], v[142:145], v[146:149], v[88:91]
	v_cvt_pk_bf16_f32 v139, v94, v95
	v_lshl_add_u64 v[134:135], v[130:131], 0, v[114:115]
	v_lshl_add_u64 v[130:131], v[130:131], 0, v[116:117]
	v_mfma_f32_16x16x32_bf16 v[88:91], v[142:145], v[150:153], v[154:157]
	v_addc_co_u32_e32 v137, vcc, 0, v133, vcc
	v_cvt_pk_bf16_f32 v140, v64, v65
	v_cvt_pk_bf16_f32 v141, v66, v67
	v_cvt_pk_bf16_f32 v142, v68, v69
	v_cvt_pk_bf16_f32 v143, v70, v71
	v_cvt_pk_bf16_f32 v144, v72, v73
	v_cvt_pk_bf16_f32 v145, v74, v75
	v_cvt_pk_bf16_f32 v146, v76, v77
	v_cvt_pk_bf16_f32 v147, v78, v79
	v_cvt_pk_bf16_f32 v148, v80, v81
	v_cvt_pk_bf16_f32 v149, v82, v83
	v_cvt_pk_bf16_f32 v150, v84, v85
	v_cvt_pk_bf16_f32 v151, v86, v87
	v_cvt_pk_bf16_f32 v152, v88, v89
	v_cvt_pk_bf16_f32 v153, v90, v91
	global_store_dwordx2 v[132:133], v[138:139], off
	global_store_dwordx2 v[136:137], v[140:141], off
	global_store_dwordx2 v[132:133], v[142:143], off offset:512
	global_store_dwordx2 v[134:135], v[144:145], off
	global_store_dwordx2 v[132:133], v[146:147], off offset:1024
	global_store_dwordx2 v[136:137], v[148:149], off offset:1024
	global_store_dwordx2 v[132:133], v[150:151], off offset:1536
	global_store_dwordx2 v[130:131], v[152:153], off
	s_add_i32 s24, s24, -2
	s_and_b64 vcc, exec, s[14:15]
	s_mov_b32 s26, s27
	s_cbranch_vccnz .LBB0_503
	s_waitcnt lgkmcnt(0)
	s_barrier
